# v29 + relaxed vmcnt (16/24) on the first two waits of the peeled first K-iteration for non-first units (epilogue stores may stay in flight)
# speedup vs baseline: 1.0055x; 1.0055x over previous
; #define PG8_STAGE(bufoff, gbase, voff) do { _Pragma("unroll") for (int _i = 0; _i < 2; ++_i) \
;         pg8_dma16((const char*)(gbase), (voff)[_i], ldsb + (unsigned)((bufoff) + _i * 8192)); } while (0)
; #define PG8_LDA(dst, b, h) do { _Pragma("unroll") for (int m = 0; m < 4; ++m) _Pragma("unroll") for (int k = 0; k < 2; ++k) dst[m][k] = *(const PG8_LAS bf16x8*)(lds + PG8_SA(b, h) + aoff + m * 2048 + k * 1024); } while (0)
; #define PG8_LDB(dst, b, h) do { _Pragma("unroll") for (int n = 0; n < 2; ++n) _Pragma("unroll") for (int k = 0; k < 2; ++k) dst[n][k] = *(const PG8_LAS bf16x8*)(lds + PG8_SB(b, h) + boff + n * 2048 + k * 1024); } while (0)
; #define PG8_MMA(ai, bj, At, Bt) do { __builtin_amdgcn_s_setprio(1); _Pragma("unroll") for (int m = 0; m < 4; ++m) _Pragma("unroll") for (int n = 0; n < 2; ++n) _Pragma("unroll") for (int k = 0; k < 2; ++k) \
;         acc[ai][bj][m][n] = __builtin_amdgcn_mfma_f32_16x16x32_bf16(Bt[n][k], At[m][k], acc[ai][bj][m][n], 0, 0, 0); __builtin_amdgcn_s_setprio(0); } while (0)
; #define PG8_WAIT_V(n) asm volatile("s_waitcnt vmcnt(" #n ")" ::: "memory")
; #define PG8_WAIT_L(n) asm volatile("s_waitcnt lgkmcnt(" #n ")" ::: "memory")
; #define PG8_BAR __builtin_amdgcn_s_barrier()
; #define PG8_SCHED __builtin_amdgcn_sched_barrier(0)
; template <class Epi, class Sched, bool ALIGN_EPI = false, bool SP2 = false>
; __device__ __forceinline__ void gemm_phase(PG8_LAS unsigned char* lds, const Gemm g, const Sched& S, const Epi& E) {
;     ...
;             PG8_LDB(B0, 0, 0); PG8_LDB(B1, 0, 1); PG8_SCHED; PG8_LDA(At, 0, 0); PG8_STAGE(PG8_SA(1, 1), a1 + hstep, voffA);
;             PG8_WAIT_V(8); PG8_WAIT_L(0); PG8_BAR; PG8_MMA(0, 0, At, B0); PG8_MMA(0, 1, At, B1); PG8_BAR; PG8_SCHED;
;             PG8_LDA(At, 0, 1); PG8_STAGE(PG8_SB(0, 0), b2, voffB); PG8_STAGE(PG8_SB(0, 1), b2 + hstep, voffB); PG8_STAGE(PG8_SA(0, 0), a2, voffA);
;             PG8_WAIT_V(8); PG8_WAIT_L(0); PG8_BAR; PG8_MMA(1, 0, At, B0); PG8_MMA(1, 1, At, B1); PG8_BAR; PG8_SCHED;
.Lpeel_body:
	ds_read_b128 v[128:131], v229
	ds_read_b128 v[132:135], v229 offset:1024
	ds_read_b128 v[136:139], v229 offset:2048
	ds_read_b128 v[140:143], v229 offset:3072
	ds_read_b128 v[144:147], v230
	ds_read_b128 v[152:155], v230 offset:1024
	ds_read_b128 v[156:159], v230 offset:2048
	ds_read_b128 v[160:163], v230 offset:3072
	s_add_i32 s58, s12, 2
	s_cmp_eq_u32 s77, s12
	s_cselect_b32 s40, s30, s72
	s_cselect_b32 s41, s31, s95
	s_cselect_b32 s36, s34, vcc_lo
	s_cselect_b32 s37, s35, vcc_hi
	s_add_u32 s12, s40, 0x80
	s_addc_u32 s13, s41, 0
	ds_read_b128 v[164:167], v208
	ds_read_b128 v[168:171], v208 offset:1024
	ds_read_b128 v[172:175], v208 offset:2048
	ds_read_b128 v[176:179], v208 offset:3072
	ds_read_b128 v[180:183], v208 offset:4096
	ds_read_b128 v[210:213], v208 offset:5120
	ds_read_b128 v[214:217], v208 offset:6144
	ds_read_b128 v[218:221], v208 offset:7168
	s_mov_b32 m0, s78
	s_nop 0
	global_load_lds_dwordx4 v148, s[10:11]
	s_mov_b32 m0, s80
	s_nop 0
	global_load_lds_dwordx4 v198, s[10:11]
	s_cmp_eq_u32 s79, 1
	s_cbranch_scc1 .Lrx8_1
	s_cmp_eq_u32 s93, 1
	s_cbranch_scc1 .Lrx16_1
	s_waitcnt vmcnt(24)
	s_branch .Lrxd_1
.Lrx16_1:
	s_waitcnt vmcnt(16)
	s_branch .Lrxd_1
.Lrx8_1:
	s_waitcnt vmcnt(8)
.Lrxd_1:
	s_waitcnt lgkmcnt(0)
	s_barrier
	s_setprio 1
	v_mfma_f32_16x16x32_bf16 v[124:127], v[128:131], v[164:167], 0
	v_mfma_f32_16x16x32_bf16 v[116:119], v[136:139], v[164:167], 0
	v_mfma_f32_16x16x32_bf16 v[108:111], v[128:131], v[172:175], 0
	v_mfma_f32_16x16x32_bf16 v[100:103], v[136:139], v[172:175], 0
	v_mfma_f32_16x16x32_bf16 v[92:95], v[128:131], v[180:183], 0
	v_mfma_f32_16x16x32_bf16 v[84:87], v[136:139], v[180:183], 0
	v_mfma_f32_16x16x32_bf16 v[76:79], v[128:131], v[214:217], 0
	v_mfma_f32_16x16x32_bf16 v[68:71], v[136:139], v[214:217], 0
	v_mfma_f32_16x16x32_bf16 v[124:127], v[132:135], v[168:171], v[124:127]
	v_mfma_f32_16x16x32_bf16 v[116:119], v[140:143], v[168:171], v[116:119]
	v_mfma_f32_16x16x32_bf16 v[108:111], v[132:135], v[176:179], v[108:111]
	v_mfma_f32_16x16x32_bf16 v[100:103], v[140:143], v[176:179], v[100:103]
	v_mfma_f32_16x16x32_bf16 v[92:95], v[132:135], v[210:213], v[92:95]
	v_mfma_f32_16x16x32_bf16 v[84:87], v[140:143], v[210:213], v[84:87]
	v_mfma_f32_16x16x32_bf16 v[76:79], v[132:135], v[218:221], v[76:79]
	v_mfma_f32_16x16x32_bf16 v[68:71], v[140:143], v[218:221], v[68:71]
	v_mfma_f32_16x16x32_bf16 v[120:123], v[144:147], v[164:167], 0
	v_mfma_f32_16x16x32_bf16 v[112:115], v[156:159], v[164:167], 0
	v_mfma_f32_16x16x32_bf16 v[104:107], v[144:147], v[172:175], 0
	v_mfma_f32_16x16x32_bf16 v[96:99], v[156:159], v[172:175], 0
	v_mfma_f32_16x16x32_bf16 v[88:91], v[144:147], v[180:183], 0
	v_mfma_f32_16x16x32_bf16 v[80:83], v[156:159], v[180:183], 0
	v_mfma_f32_16x16x32_bf16 v[72:75], v[144:147], v[214:217], 0
	v_mfma_f32_16x16x32_bf16 v[64:67], v[156:159], v[214:217], 0
	v_mfma_f32_16x16x32_bf16 v[120:123], v[152:155], v[168:171], v[120:123]
	v_mfma_f32_16x16x32_bf16 v[112:115], v[160:163], v[168:171], v[112:115]
	v_mfma_f32_16x16x32_bf16 v[104:107], v[152:155], v[176:179], v[104:107]
	v_mfma_f32_16x16x32_bf16 v[96:99], v[160:163], v[176:179], v[96:99]
	v_mfma_f32_16x16x32_bf16 v[88:91], v[152:155], v[210:213], v[88:91]
	v_mfma_f32_16x16x32_bf16 v[80:83], v[160:163], v[210:213], v[80:83]
	v_mfma_f32_16x16x32_bf16 v[72:75], v[152:155], v[218:221], v[72:75]
	v_mfma_f32_16x16x32_bf16 v[64:67], v[160:163], v[218:221], v[64:67]
	s_setprio 0
	s_barrier
	ds_read_b128 v[164:167], v208 offset:16384
	ds_read_b128 v[168:171], v208 offset:17408
	ds_read_b128 v[172:175], v208 offset:18432
	ds_read_b128 v[176:179], v208 offset:19456
	ds_read_b128 v[180:183], v208 offset:20480
	ds_read_b128 v[210:213], v208 offset:21504
	ds_read_b128 v[214:217], v208 offset:22528
	ds_read_b128 v[218:221], v208 offset:23552
	s_mov_b32 m0, s50
	s_nop 0
	global_load_lds_dwordx4 v151, s[36:37]
	s_mov_b32 m0, s51
	s_nop 0
	global_load_lds_dwordx4 v199, s[36:37]
	s_add_u32 s4, s36, s47
	s_addc_u32 s5, s37, 0
	s_mov_b32 m0, s61
	s_nop 0
	global_load_lds_dwordx4 v151, s[4:5]
	s_mov_b32 m0, s62
	s_nop 0
	global_load_lds_dwordx4 v199, s[4:5]
	s_mov_b32 m0, s49
	s_nop 0
	global_load_lds_dwordx4 v148, s[40:41]
	s_mov_b32 m0, s63
	s_nop 0
	global_load_lds_dwordx4 v198, s[40:41]
	s_cmp_eq_u32 s79, 1
	s_cbranch_scc1 .Lrx8_2
	s_cmp_eq_u32 s93, 1
	s_cbranch_scc1 .Lrx16_2
	s_waitcnt vmcnt(24)
	s_branch .Lrxd_2

; #define PG8_STAGE(bufoff, gbase, voff) do { _Pragma("unroll") for (int _i = 0; _i < 2; ++_i) \
;         pg8_dma16((const char*)(gbase), (voff)[_i], ldsb + (unsigned)((bufoff) + _i * 8192)); } while (0)
; #define PG8_LDA(dst, b, h) do { _Pragma("unroll") for (int m = 0; m < 4; ++m) _Pragma("unroll") for (int k = 0; k < 2; ++k) dst[m][k] = *(const PG8_LAS bf16x8*)(lds + PG8_SA(b, h) + aoff + m * 2048 + k * 1024); } while (0)
; #define PG8_LDB(dst, b, h) do { _Pragma("unroll") for (int n = 0; n < 2; ++n) _Pragma("unroll") for (int k = 0; k < 2; ++k) dst[n][k] = *(const PG8_LAS bf16x8*)(lds + PG8_SB(b, h) + boff + n * 2048 + k * 1024); } while (0)
; #define PG8_MMA(ai, bj, At, Bt) do { __builtin_amdgcn_s_setprio(1); _Pragma("unroll") for (int m = 0; m < 4; ++m) _Pragma("unroll") for (int n = 0; n < 2; ++n) _Pragma("unroll") for (int k = 0; k < 2; ++k) \
;         acc[ai][bj][m][n] = __builtin_amdgcn_mfma_f32_16x16x32_bf16(Bt[n][k], At[m][k], acc[ai][bj][m][n], 0, 0, 0); __builtin_amdgcn_s_setprio(0); } while (0)
; #define PG8_WAIT_V(n) asm volatile("s_waitcnt vmcnt(" #n ")" ::: "memory")
; #define PG8_WAIT_L(n) asm volatile("s_waitcnt lgkmcnt(" #n ")" ::: "memory")
; #define PG8_BAR __builtin_amdgcn_s_barrier()
; #define PG8_SCHED __builtin_amdgcn_sched_barrier(0)
; template <class Epi, class Sched, bool ALIGN_EPI = false, bool SP2 = false>
; __device__ __forceinline__ void gemm_phase(PG8_LAS unsigned char* lds, const Gemm g, const Sched& S, const Epi& E) {
;     ...
;             PG8_WAIT_V(8); PG8_WAIT_L(0); PG8_BAR; PG8_MMA(1, 0, At, B0); PG8_MMA(1, 1, At, B1); PG8_BAR; PG8_SCHED;
;             PG8_LDB(B0, 1, 0); PG8_LDB(B1, 1, 1); PG8_SCHED; PG8_LDA(At, 1, 0); PG8_STAGE(PG8_SA(0, 1), a2 + hstep, voffA);
;             PG8_WAIT_V(8); PG8_WAIT_L(0); PG8_BAR; PG8_MMA(0, 0, At, B0); PG8_MMA(0, 1, At, B1); PG8_BAR; PG8_SCHED;
.Lrxd_2:
	s_waitcnt lgkmcnt(0)
	s_barrier
	s_setprio 1
	v_mfma_f32_16x16x32_bf16 v[60:63], v[128:131], v[164:167], 0
	v_mfma_f32_16x16x32_bf16 v[52:55], v[136:139], v[164:167], 0
	v_mfma_f32_16x16x32_bf16 v[44:47], v[128:131], v[172:175], 0
	v_mfma_f32_16x16x32_bf16 v[36:39], v[136:139], v[172:175], 0
	v_mfma_f32_16x16x32_bf16 v[28:31], v[128:131], v[180:183], 0
	v_mfma_f32_16x16x32_bf16 v[20:23], v[136:139], v[180:183], 0
	v_mfma_f32_16x16x32_bf16 v[12:15], v[128:131], v[214:217], 0
	v_mfma_f32_16x16x32_bf16 v[4:7], v[136:139], v[214:217], 0
	v_mfma_f32_16x16x32_bf16 v[60:63], v[132:135], v[168:171], v[60:63]
	v_mfma_f32_16x16x32_bf16 v[52:55], v[140:143], v[168:171], v[52:55]
	v_mfma_f32_16x16x32_bf16 v[44:47], v[132:135], v[176:179], v[44:47]
	v_mfma_f32_16x16x32_bf16 v[36:39], v[140:143], v[176:179], v[36:39]
	v_mfma_f32_16x16x32_bf16 v[28:31], v[132:135], v[210:213], v[28:31]
	v_mfma_f32_16x16x32_bf16 v[20:23], v[140:143], v[210:213], v[20:23]
	v_mfma_f32_16x16x32_bf16 v[12:15], v[132:135], v[218:221], v[12:15]
	v_mfma_f32_16x16x32_bf16 v[4:7], v[140:143], v[218:221], v[4:7]
	v_mfma_f32_16x16x32_bf16 v[56:59], v[144:147], v[164:167], 0
	v_mfma_f32_16x16x32_bf16 v[48:51], v[156:159], v[164:167], 0
	v_mfma_f32_16x16x32_bf16 v[40:43], v[144:147], v[172:175], 0
	v_mfma_f32_16x16x32_bf16 v[32:35], v[156:159], v[172:175], 0
	v_mfma_f32_16x16x32_bf16 v[24:27], v[144:147], v[180:183], 0
	v_mfma_f32_16x16x32_bf16 v[16:19], v[156:159], v[180:183], 0
	v_mfma_f32_16x16x32_bf16 v[8:11], v[144:147], v[214:217], 0
	v_mfma_f32_16x16x32_bf16 v[0:3], v[156:159], v[214:217], 0
	v_mfma_f32_16x16x32_bf16 v[56:59], v[152:155], v[168:171], v[56:59]
	v_mfma_f32_16x16x32_bf16 v[48:51], v[160:163], v[168:171], v[48:51]
	v_mfma_f32_16x16x32_bf16 v[40:43], v[152:155], v[176:179], v[40:43]
	v_mfma_f32_16x16x32_bf16 v[32:35], v[160:163], v[176:179], v[32:35]
	v_mfma_f32_16x16x32_bf16 v[24:27], v[152:155], v[210:213], v[24:27]
	v_mfma_f32_16x16x32_bf16 v[16:19], v[160:163], v[210:213], v[16:19]
	v_mfma_f32_16x16x32_bf16 v[8:11], v[152:155], v[218:221], v[8:11]
	v_mfma_f32_16x16x32_bf16 v[0:3], v[160:163], v[218:221], v[0:3]
	s_setprio 0
	s_barrier
	ds_read_b128 v[128:131], v231
	ds_read_b128 v[132:135], v231 offset:1024
	ds_read_b128 v[136:139], v231 offset:2048
	ds_read_b128 v[140:143], v231 offset:3072
	ds_read_b128 v[144:147], v232
	ds_read_b128 v[152:155], v232 offset:1024
	ds_read_b128 v[156:159], v232 offset:2048
	ds_read_b128 v[160:163], v232 offset:3072
	ds_read_b128 v[164:167], v208 offset:32768
	ds_read_b128 v[168:171], v208 offset:33792
	ds_read_b128 v[172:175], v208 offset:34816
	ds_read_b128 v[176:179], v208 offset:35840
	ds_read_b128 v[180:183], v208 offset:36864
	ds_read_b128 v[210:213], v208 offset:37888
	ds_read_b128 v[214:217], v208 offset:38912
	ds_read_b128 v[218:221], v208 offset:39936
	s_add_u32 s4, s40, s47
	s_addc_u32 s5, s41, 0
	s_mov_b32 m0, s64
	s_nop 0
	global_load_lds_dwordx4 v148, s[4:5]
	s_mov_b32 m0, s65
	s_nop 0
	global_load_lds_dwordx4 v198, s[4:5]
	s_waitcnt vmcnt(8)
	s_waitcnt lgkmcnt(0)
	s_barrier
	s_setprio 1
	v_mfma_f32_16x16x32_bf16 v[124:127], v[128:131], v[164:167], v[124:127]
	v_mfma_f32_16x16x32_bf16 v[116:119], v[136:139], v[164:167], v[116:119]
	v_mfma_f32_16x16x32_bf16 v[108:111], v[128:131], v[172:175], v[108:111]
	v_mfma_f32_16x16x32_bf16 v[100:103], v[136:139], v[172:175], v[100:103]
	v_mfma_f32_16x16x32_bf16 v[92:95], v[128:131], v[180:183], v[92:95]
	v_mfma_f32_16x16x32_bf16 v[84:87], v[136:139], v[180:183], v[84:87]
	v_mfma_f32_16x16x32_bf16 v[76:79], v[128:131], v[214:217], v[76:79]
	v_mfma_f32_16x16x32_bf16 v[68:71], v[136:139], v[214:217], v[68:71]
	v_mfma_f32_16x16x32_bf16 v[124:127], v[132:135], v[168:171], v[124:127]
	v_mfma_f32_16x16x32_bf16 v[116:119], v[140:143], v[168:171], v[116:119]
	v_mfma_f32_16x16x32_bf16 v[108:111], v[132:135], v[176:179], v[108:111]
	v_mfma_f32_16x16x32_bf16 v[100:103], v[140:143], v[176:179], v[100:103]
	v_mfma_f32_16x16x32_bf16 v[92:95], v[132:135], v[210:213], v[92:95]
	v_mfma_f32_16x16x32_bf16 v[84:87], v[140:143], v[210:213], v[84:87]
	v_mfma_f32_16x16x32_bf16 v[76:79], v[132:135], v[218:221], v[76:79]
	v_mfma_f32_16x16x32_bf16 v[68:71], v[140:143], v[218:221], v[68:71]
	v_mfma_f32_16x16x32_bf16 v[120:123], v[144:147], v[164:167], v[120:123]
	v_mfma_f32_16x16x32_bf16 v[112:115], v[156:159], v[164:167], v[112:115]
	v_mfma_f32_16x16x32_bf16 v[104:107], v[144:147], v[172:175], v[104:107]
	v_mfma_f32_16x16x32_bf16 v[96:99], v[156:159], v[172:175], v[96:99]
	v_mfma_f32_16x16x32_bf16 v[88:91], v[144:147], v[180:183], v[88:91]
	v_mfma_f32_16x16x32_bf16 v[80:83], v[156:159], v[180:183], v[80:83]
	v_mfma_f32_16x16x32_bf16 v[72:75], v[144:147], v[214:217], v[72:75]
	v_mfma_f32_16x16x32_bf16 v[64:67], v[156:159], v[214:217], v[64:67]
	v_mfma_f32_16x16x32_bf16 v[120:123], v[152:155], v[168:171], v[120:123]
	v_mfma_f32_16x16x32_bf16 v[112:115], v[160:163], v[168:171], v[112:115]
	v_mfma_f32_16x16x32_bf16 v[104:107], v[152:155], v[176:179], v[104:107]
	v_mfma_f32_16x16x32_bf16 v[96:99], v[160:163], v[176:179], v[96:99]
	v_mfma_f32_16x16x32_bf16 v[88:91], v[152:155], v[210:213], v[88:91]
	v_mfma_f32_16x16x32_bf16 v[80:83], v[160:163], v[210:213], v[80:83]
	v_mfma_f32_16x16x32_bf16 v[72:75], v[152:155], v[218:221], v[72:75]
	v_mfma_f32_16x16x32_bf16 v[64:67], v[160:163], v[218:221], v[64:67]
	s_setprio 0
	s_barrier
; #define PG8_STAGE(bufoff, gbase, voff) do { _Pragma("unroll") for (int _i = 0; _i < 2; ++_i) \
;         pg8_dma16((const char*)(gbase), (voff)[_i], ldsb + (unsigned)((bufoff) + _i * 8192)); } while (0)
; #define PG8_LDA(dst, b, h) do { _Pragma("unroll") for (int m = 0; m < 4; ++m) _Pragma("unroll") for (int k = 0; k < 2; ++k) dst[m][k] = *(const PG8_LAS bf16x8*)(lds + PG8_SA(b, h) + aoff + m * 2048 + k * 1024); } while (0)
; #define PG8_MMA(ai, bj, At, Bt) do { __builtin_amdgcn_s_setprio(1); _Pragma("unroll") for (int m = 0; m < 4; ++m) _Pragma("unroll") for (int n = 0; n < 2; ++n) _Pragma("unroll") for (int k = 0; k < 2; ++k) \
;         acc[ai][bj][m][n] = __builtin_amdgcn_mfma_f32_16x16x32_bf16(Bt[n][k], At[m][k], acc[ai][bj][m][n], 0, 0, 0); __builtin_amdgcn_s_setprio(0); } while (0)
; #define PG8_WAIT_V(n) asm volatile("s_waitcnt vmcnt(" #n ")" ::: "memory")
; #define PG8_WAIT_L(n) asm volatile("s_waitcnt lgkmcnt(" #n ")" ::: "memory")
; #define PG8_BAR __builtin_amdgcn_s_barrier()
; #define PG8_SCHED __builtin_amdgcn_sched_barrier(0)
; template <class Epi, class Sched, bool ALIGN_EPI = false, bool SP2 = false>
; __device__ __forceinline__ void gemm_phase(PG8_LAS unsigned char* lds, const Gemm g, const Sched& S, const Epi& E) {
;     ...
;             PG8_LDA(At, 1, 1); PG8_STAGE(PG8_SB(1, 0), b3, voffB); PG8_STAGE(PG8_SB(1, 1), b3 + hstep, voffB); PG8_STAGE(PG8_SA(1, 0), a3, voffA);
;             PG8_WAIT_V(8); PG8_WAIT_L(0); PG8_BAR; PG8_MMA(1, 0, At, B0); PG8_MMA(1, 1, At, B1); PG8_BAR; PG8_SCHED;
	ds_read_b128 v[164:167], v208 offset:49152
	ds_read_b128 v[168:171], v208 offset:50176
	ds_read_b128 v[172:175], v208 offset:51200
	ds_read_b128 v[176:179], v208 offset:52224
	ds_read_b128 v[180:183], v208 offset:53248
	ds_read_b128 v[210:213], v208 offset:54272
	ds_read_b128 v[214:217], v208 offset:55296
	ds_read_b128 v[218:221], v208 offset:56320
	s_add_u32 s4, s36, 0x80
	s_addc_u32 s5, s37, 0
	s_mov_b32 m0, s67
	s_nop 0
	global_load_lds_dwordx4 v151, s[4:5]
	s_mov_b32 m0, s70
	s_nop 0
	global_load_lds_dwordx4 v199, s[4:5]
	s_add_u32 s4, s4, s47
	s_addc_u32 s5, s5, 0
	s_mov_b32 m0, s75
	s_nop 0
	global_load_lds_dwordx4 v151, s[4:5]
	s_mov_b32 m0, s76
	s_nop 0
	global_load_lds_dwordx4 v199, s[4:5]
	s_mov_b32 m0, s71
	s_nop 0
	global_load_lds_dwordx4 v148, s[12:13]
	s_mov_b32 m0, s74
	s_nop 0
	global_load_lds_dwordx4 v198, s[12:13]
	s_add_u32 s72, s72, 0x100
	s_addc_u32 s95, s95, 0
	s_add_u32 vcc_lo, vcc_lo, 0x100
	s_addc_u32 vcc_hi, vcc_hi, 0
	s_add_u32 s10, s10, 0x100
	s_addc_u32 s11, s11, 0
	s_mov_b32 s12, s58
	s_cmp_ge_u32 s58, s60
	s_waitcnt vmcnt(8)
	s_waitcnt lgkmcnt(0)
	s_barrier
	s_setprio 1
	v_mfma_f32_16x16x32_bf16 v[60:63], v[128:131], v[164:167], v[60:63]
	v_mfma_f32_16x16x32_bf16 v[52:55], v[136:139], v[164:167], v[52:55]
	v_mfma_f32_16x16x32_bf16 v[44:47], v[128:131], v[172:175], v[44:47]
	v_mfma_f32_16x16x32_bf16 v[36:39], v[136:139], v[172:175], v[36:39]
	v_mfma_f32_16x16x32_bf16 v[28:31], v[128:131], v[180:183], v[28:31]
	v_mfma_f32_16x16x32_bf16 v[20:23], v[136:139], v[180:183], v[20:23]
	v_mfma_f32_16x16x32_bf16 v[12:15], v[128:131], v[214:217], v[12:15]
	v_mfma_f32_16x16x32_bf16 v[4:7], v[136:139], v[214:217], v[4:7]
	v_mfma_f32_16x16x32_bf16 v[60:63], v[132:135], v[168:171], v[60:63]
	v_mfma_f32_16x16x32_bf16 v[52:55], v[140:143], v[168:171], v[52:55]
	v_mfma_f32_16x16x32_bf16 v[44:47], v[132:135], v[176:179], v[44:47]
	v_mfma_f32_16x16x32_bf16 v[36:39], v[140:143], v[176:179], v[36:39]
	v_mfma_f32_16x16x32_bf16 v[28:31], v[132:135], v[210:213], v[28:31]
	v_mfma_f32_16x16x32_bf16 v[20:23], v[140:143], v[210:213], v[20:23]
	v_mfma_f32_16x16x32_bf16 v[12:15], v[132:135], v[218:221], v[12:15]
	v_mfma_f32_16x16x32_bf16 v[4:7], v[140:143], v[218:221], v[4:7]
	v_mfma_f32_16x16x32_bf16 v[56:59], v[144:147], v[164:167], v[56:59]
	v_mfma_f32_16x16x32_bf16 v[48:51], v[156:159], v[164:167], v[48:51]
	v_mfma_f32_16x16x32_bf16 v[40:43], v[144:147], v[172:175], v[40:43]
	v_mfma_f32_16x16x32_bf16 v[32:35], v[156:159], v[172:175], v[32:35]
	v_mfma_f32_16x16x32_bf16 v[24:27], v[144:147], v[180:183], v[24:27]
	v_mfma_f32_16x16x32_bf16 v[16:19], v[156:159], v[180:183], v[16:19]
	v_mfma_f32_16x16x32_bf16 v[8:11], v[144:147], v[214:217], v[8:11]
	v_mfma_f32_16x16x32_bf16 v[0:3], v[156:159], v[214:217], v[0:3]
	v_mfma_f32_16x16x32_bf16 v[56:59], v[152:155], v[168:171], v[56:59]
	v_mfma_f32_16x16x32_bf16 v[48:51], v[160:163], v[168:171], v[48:51]
	v_mfma_f32_16x16x32_bf16 v[40:43], v[152:155], v[176:179], v[40:43]
	v_mfma_f32_16x16x32_bf16 v[32:35], v[160:163], v[176:179], v[32:35]
	v_mfma_f32_16x16x32_bf16 v[24:27], v[152:155], v[210:213], v[24:27]
	v_mfma_f32_16x16x32_bf16 v[16:19], v[160:163], v[210:213], v[16:19]
	v_mfma_f32_16x16x32_bf16 v[8:11], v[152:155], v[218:221], v[8:11]
	v_mfma_f32_16x16x32_bf16 v[0:3], v[160:163], v[218:221], v[0:3]
	s_setprio 0
	s_barrier
	s_cbranch_scc0 .LBB0_305
	s_branch .Lml_exit2
